# attention: next-block QK MFMAs deferred into exp/PV block (early K-fragment ring reads) so MFMA overlaps softmax VALU within each wave
# speedup vs baseline: 1.0586x; 1.0088x over previous
.LBB0_836:
	s_cmp_le_i32 s1, s72
	s_cselect_b64 s[2:3], -1, 0
	s_cmp_lg_u32 s18, s1
	s_cselect_b64 s[16:17], -1, 0
	s_or_b64 s[16:17], s[8:9], s[16:17]
	s_and_b64 s[2:3], s[2:3], s[16:17]
	s_and_b64 vcc, exec, s[2:3]
	s_cbranch_vccz .Lattn_nok1
	s_mul_i32 s22, s19, 0x3000
	v_add_u32_e32 v253, s22, v183
	ds_read_b128 v[206:209], v253
	ds_read_b128 v[210:213], v253 offset:512
	ds_read_b128 v[214:217], v253 offset:2048
	ds_read_b128 v[218:221], v253 offset:2560
	ds_read_b128 v[222:225], v253 offset:4096
	ds_read_b128 v[226:229], v253 offset:4608
	ds_read_b128 v[236:239], v253 offset:6144
	ds_read_b128 v[240:243], v253 offset:6656
	ds_read_b128 v[248:251], v253 offset:8192
.Lattn_nok1:
	s_cmp_gt_i32 s1, s72
	s_cbranch_scc0 .LBB0_843

.LBB0_841:
	s_and_saveexec_b64 s[14:15], s[2:3]
	s_cbranch_execnz .LBB0_861
	s_branch .LBB0_870
.LBB0_843:
	s_cmp_lt_i32 s1, s72
	s_cbranch_scc1 .LBB0_845
	v_add_u32_e32 v152, s73, v182
	v_add_u32_e32 v153, 32, v152
	v_cmp_le_i32_e32 vcc, v153, v172
	v_add_u32_e32 v153, 33, v152
	s_nop 0
	v_cndmask_b32_e32 v64, v200, v64, vcc
	v_cmp_lt_i32_e32 vcc, v152, v172
	s_nop 1
	v_cndmask_b32_e32 v49, v200, v49, vcc
	v_cmp_le_i32_e32 vcc, v152, v172
	s_nop 1
	v_cndmask_b32_e32 v48, v200, v48, vcc
	v_cmp_le_i32_e32 vcc, v153, v172
	v_add_u32_e32 v153, 2, v152
	s_nop 0
	v_cndmask_b32_e32 v65, v200, v65, vcc
	v_cmp_le_i32_e32 vcc, v153, v172
	v_add_u32_e32 v153, 34, v152
	s_nop 0
	v_cndmask_b32_e32 v50, v200, v50, vcc
	v_cmp_le_i32_e32 vcc, v153, v172
	v_add_u32_e32 v153, 3, v152
	s_nop 0
	v_cndmask_b32_e32 v66, v200, v66, vcc
	v_cmp_le_i32_e32 vcc, v153, v172
	v_add_u32_e32 v153, 35, v152
	s_nop 0
	v_cndmask_b32_e32 v51, v200, v51, vcc
	v_cmp_le_i32_e32 vcc, v153, v172
	v_add_u32_e32 v153, 8, v152
	s_nop 0
	v_cndmask_b32_e32 v67, v200, v67, vcc
	v_cmp_le_i32_e32 vcc, v153, v172
	v_add_u32_e32 v153, 40, v152
	s_nop 0
	v_cndmask_b32_e32 v52, v200, v52, vcc
	v_cmp_le_i32_e32 vcc, v153, v172
	v_add_u32_e32 v153, 9, v152
	s_nop 0
	v_cndmask_b32_e32 v68, v200, v68, vcc
	v_cmp_le_i32_e32 vcc, v153, v172
	v_add_u32_e32 v153, 41, v152
	s_nop 0
	v_cndmask_b32_e32 v53, v200, v53, vcc
	v_cmp_le_i32_e32 vcc, v153, v172
	v_add_u32_e32 v153, 10, v152
	s_nop 0
	v_cndmask_b32_e32 v69, v200, v69, vcc
	v_cmp_le_i32_e32 vcc, v153, v172
	v_add_u32_e32 v153, 42, v152
	s_nop 0
	v_cndmask_b32_e32 v54, v200, v54, vcc
	v_cmp_le_i32_e32 vcc, v153, v172
	v_add_u32_e32 v153, 11, v152
	s_nop 0
	v_cndmask_b32_e32 v70, v200, v70, vcc
	v_cmp_le_i32_e32 vcc, v153, v172
	v_add_u32_e32 v153, 43, v152
	s_nop 0
	v_cndmask_b32_e32 v55, v200, v55, vcc
	v_cmp_le_i32_e32 vcc, v153, v172
	v_add_u32_e32 v153, 16, v152
	s_nop 0
	v_cndmask_b32_e32 v71, v200, v71, vcc
	v_cmp_le_i32_e32 vcc, v153, v172
	v_add_u32_e32 v153, 48, v152
	s_nop 0
	v_cndmask_b32_e32 v56, v200, v56, vcc
	v_cmp_le_i32_e32 vcc, v153, v172
	v_add_u32_e32 v153, 17, v152
	s_nop 0
	v_cndmask_b32_e32 v72, v200, v72, vcc
	v_cmp_le_i32_e32 vcc, v153, v172
	v_add_u32_e32 v153, 49, v152
	s_nop 0
	v_cndmask_b32_e32 v57, v200, v57, vcc
	v_cmp_le_i32_e32 vcc, v153, v172
	v_add_u32_e32 v153, 18, v152
	s_nop 0
	v_cndmask_b32_e32 v73, v200, v73, vcc
	v_cmp_le_i32_e32 vcc, v153, v172
	v_add_u32_e32 v153, 50, v152
	s_nop 0
	v_cndmask_b32_e32 v58, v200, v58, vcc
	v_cmp_le_i32_e32 vcc, v153, v172
	v_add_u32_e32 v153, 19, v152
	s_nop 0
	v_cndmask_b32_e32 v74, v200, v74, vcc
	v_cmp_le_i32_e32 vcc, v153, v172
	v_add_u32_e32 v153, 51, v152
	s_nop 0
	v_cndmask_b32_e32 v59, v200, v59, vcc
	v_cmp_le_i32_e32 vcc, v153, v172
	v_add_u32_e32 v153, 24, v152
	s_nop 0
	v_cndmask_b32_e32 v75, v200, v75, vcc
	v_cmp_le_i32_e32 vcc, v153, v172
	v_add_u32_e32 v153, 56, v152
	s_nop 0
	v_cndmask_b32_e32 v60, v200, v60, vcc
	v_cmp_le_i32_e32 vcc, v153, v172
	v_add_u32_e32 v153, 25, v152
	s_nop 0
	v_cndmask_b32_e32 v76, v200, v76, vcc
	v_cmp_le_i32_e32 vcc, v153, v172
	v_add_u32_e32 v153, 57, v152
	s_nop 0
	v_cndmask_b32_e32 v61, v200, v61, vcc
	v_cmp_le_i32_e32 vcc, v153, v172
	v_add_u32_e32 v153, 26, v152
	s_nop 0
	v_cndmask_b32_e32 v77, v200, v77, vcc
	v_cmp_le_i32_e32 vcc, v153, v172
	v_add_u32_e32 v153, 58, v152
	s_nop 0
	v_cndmask_b32_e32 v62, v200, v62, vcc
	v_cmp_le_i32_e32 vcc, v153, v172
	v_add_u32_e32 v153, 27, v152
	v_add_u32_e32 v152, 59, v152
	v_cndmask_b32_e32 v78, v200, v78, vcc
	v_cmp_le_i32_e32 vcc, v153, v172
	s_nop 1
	v_cndmask_b32_e32 v63, v200, v63, vcc
	v_cmp_le_i32_e32 vcc, v152, v172
	s_nop 1
	v_cndmask_b32_e32 v79, v200, v79, vcc

.LBB0_855:
	s_and_b64 vcc, exec, s[2:3]
	s_cbranch_vccnz .Lattn_855i
	v_exp_f32_e32 v48, v48
	v_exp_f32_e32 v49, v49
	v_exp_f32_e32 v50, v50
	v_exp_f32_e32 v51, v51
	v_exp_f32_e32 v52, v52
	v_exp_f32_e32 v53, v53
	v_exp_f32_e32 v54, v54
	v_exp_f32_e32 v55, v55
	v_lshl_add_u32 v205, s62, 13, v202
	v_cvt_pk_bf16_f32 v152, v48, v49
	v_add_f32_e32 v230, v230, v48
	v_add_f32_e32 v252, v252, v49
	v_cvt_pk_bf16_f32 v153, v50, v51
	v_add_f32_e32 v230, v230, v50
	v_add_f32_e32 v252, v252, v51
	v_cvt_pk_bf16_f32 v154, v52, v53
	v_add_f32_e32 v230, v230, v52
	v_add_f32_e32 v252, v252, v53
	v_cvt_pk_bf16_f32 v155, v54, v55
	v_add_f32_e32 v230, v230, v54
	v_add_f32_e32 v252, v252, v55
	ds_read_b64_tr_b16 v[156:157], v205 offset:36864
	ds_read_b64_tr_b16 v[158:159], v205 offset:37376
	v_exp_f32_e32 v56, v56
	v_exp_f32_e32 v57, v57
	v_exp_f32_e32 v58, v58
	s_waitcnt lgkmcnt(0)
	v_mfma_f32_32x32x16_bf16 v[0:15], v[152:155], v[156:159], v[0:15]
	ds_read_b64_tr_b16 v[156:157], v205 offset:37888
	ds_read_b64_tr_b16 v[160:161], v205 offset:40960
	ds_read_b64_tr_b16 v[162:163], v205 offset:41472
	ds_read_b64_tr_b16 v[158:159], v205 offset:38400
	v_exp_f32_e32 v59, v59
	v_exp_f32_e32 v60, v60
	v_exp_f32_e32 v61, v61
	v_exp_f32_e32 v62, v62
	v_exp_f32_e32 v63, v63
	s_mov_b32 s46, s44
	s_mov_b32 s47, s44
	s_mov_b32 s45, s44
	v_mov_b64_e32 v[166:167], s[46:47]
	v_mov_b64_e32 v[164:165], s[44:45]
	s_waitcnt lgkmcnt(1)
	v_mfma_f32_32x32x16_bf16 v[16:31], v[152:155], v[160:163], v[16:31]
	v_cvt_pk_bf16_f32 v160, v56, v57
	v_add_f32_e32 v230, v230, v56
	v_add_f32_e32 v252, v252, v57
	v_cvt_pk_bf16_f32 v161, v58, v59
	v_add_f32_e32 v230, v230, v58
	v_add_f32_e32 v252, v252, v59
	v_cvt_pk_bf16_f32 v162, v60, v61
	v_add_f32_e32 v230, v230, v60
	v_add_f32_e32 v252, v252, v61
	v_cvt_pk_bf16_f32 v163, v62, v63
	v_add_f32_e32 v230, v230, v62
	v_add_f32_e32 v252, v252, v63
	v_exp_f32_e32 v64, v64
	v_exp_f32_e32 v65, v65
	v_exp_f32_e32 v66, v66
	ds_read_b64_tr_b16 v[152:153], v205 offset:41984
	ds_read_b64_tr_b16 v[154:155], v205 offset:42496
	v_exp_f32_e32 v67, v67
	v_exp_f32_e32 v68, v68
	v_exp_f32_e32 v69, v69
	v_exp_f32_e32 v70, v70
	v_exp_f32_e32 v71, v71
	v_exp_f32_e32 v72, v72
	s_waitcnt lgkmcnt(2)
	v_mfma_f32_32x32x16_bf16 v[0:15], v[160:163], v[156:159], v[0:15]
	ds_read_b64_tr_b16 v[156:157], v205 offset:38912
	ds_read_b64_tr_b16 v[158:159], v205 offset:39424
	v_exp_f32_e32 v73, v73
	v_exp_f32_e32 v74, v74
	v_exp_f32_e32 v75, v75
	v_exp_f32_e32 v76, v76
	v_exp_f32_e32 v77, v77
	v_exp_f32_e32 v78, v78
	s_waitcnt lgkmcnt(2)
	v_mfma_f32_32x32x16_bf16 v[16:31], v[160:163], v[152:155], v[16:31]
	v_cvt_pk_bf16_f32 v152, v64, v65
	v_add_f32_e32 v230, v230, v64
	v_add_f32_e32 v252, v252, v65
	v_cvt_pk_bf16_f32 v153, v66, v67
	v_add_f32_e32 v230, v230, v66
	v_add_f32_e32 v252, v252, v67
	v_cvt_pk_bf16_f32 v154, v68, v69
	v_add_f32_e32 v230, v230, v68
	v_add_f32_e32 v252, v252, v69
	v_cvt_pk_bf16_f32 v155, v70, v71
	v_add_f32_e32 v230, v230, v70
	v_add_f32_e32 v252, v252, v71
	v_exp_f32_e32 v79, v79
	s_waitcnt lgkmcnt(0)
	v_mfma_f32_32x32x16_bf16 v[0:15], v[152:155], v[156:159], v[0:15]
	ds_read_b64_tr_b16 v[156:157], v205 offset:43008
	ds_read_b64_tr_b16 v[158:159], v205 offset:43520
	ds_read_b64_tr_b16 v[160:161], v205 offset:39936
	ds_read_b64_tr_b16 v[162:163], v205 offset:40448
	s_waitcnt lgkmcnt(2)
	v_mfma_f32_32x32x16_bf16 v[16:31], v[152:155], v[156:159], v[16:31]
	v_cvt_pk_bf16_f32 v156, v72, v73
	v_add_f32_e32 v230, v230, v72
	v_add_f32_e32 v252, v252, v73
	v_cvt_pk_bf16_f32 v157, v74, v75
	v_add_f32_e32 v230, v230, v74
	v_add_f32_e32 v252, v252, v75
	v_cvt_pk_bf16_f32 v158, v76, v77
	v_add_f32_e32 v230, v230, v76
	v_add_f32_e32 v252, v252, v77
	v_cvt_pk_bf16_f32 v159, v78, v79
	v_add_f32_e32 v230, v230, v78
	v_add_f32_e32 v252, v252, v79
	ds_read_b64_tr_b16 v[152:153], v205 offset:44032
	ds_read_b64_tr_b16 v[154:155], v205 offset:44544
	s_waitcnt lgkmcnt(2)
	v_mfma_f32_32x32x16_bf16 v[0:15], v[156:159], v[160:163], v[0:15]
	s_waitcnt lgkmcnt(0)
	v_mfma_f32_32x32x16_bf16 v[16:31], v[156:159], v[152:155], v[16:31]
.Lattn_855_end:
	s_andn2_b64 vcc, exec, s[14:15]
	s_cbranch_vccnz .LBB0_839

.LBB0_860:
	s_and_b64 vcc, exec, s[2:3]
	s_cbranch_vccz .Lattn_860o
	s_mul_i32 s22, s68, 0x3000
	v_add_u32_e32 v253, s22, v183
	ds_read_b128 v[206:209], v253
	ds_read_b128 v[210:213], v253 offset:512
	ds_read_b128 v[214:217], v253 offset:2048
	ds_read_b128 v[218:221], v253 offset:2560
	ds_read_b128 v[222:225], v253 offset:4096
	ds_read_b128 v[226:229], v253 offset:4608
	ds_read_b128 v[236:239], v253 offset:6144
	ds_read_b128 v[240:243], v253 offset:6656
	ds_read_b128 v[248:251], v253 offset:8192
	s_and_saveexec_b64 s[14:15], s[2:3]
	s_branch .LBB0_861

.LBB0_869:
	s_and_b64 vcc, exec, s[16:17]
	s_cbranch_vccnz .Lattn_869i
	v_exp_f32_e32 v96, v96
	v_exp_f32_e32 v97, v97
	v_exp_f32_e32 v98, v98
	v_exp_f32_e32 v99, v99
	v_exp_f32_e32 v100, v100
	v_exp_f32_e32 v101, v101
	v_exp_f32_e32 v102, v102
	v_exp_f32_e32 v103, v103
	v_lshl_add_u32 v205, s19, 13, v202
	v_cvt_pk_bf16_f32 v152, v96, v97
	v_add_f32_e32 v230, v230, v96
	v_add_f32_e32 v252, v252, v97
	v_cvt_pk_bf16_f32 v153, v98, v99
	v_add_f32_e32 v230, v230, v98
	v_add_f32_e32 v252, v252, v99
	v_cvt_pk_bf16_f32 v154, v100, v101
	v_add_f32_e32 v230, v230, v100
	v_add_f32_e32 v252, v252, v101
	v_cvt_pk_bf16_f32 v155, v102, v103
	v_add_f32_e32 v230, v230, v102
	v_add_f32_e32 v252, v252, v103
	ds_read_b64_tr_b16 v[156:157], v205 offset:36864
	ds_read_b64_tr_b16 v[158:159], v205 offset:37376
	v_exp_f32_e32 v104, v104
	v_exp_f32_e32 v105, v105
	v_exp_f32_e32 v106, v106
	s_waitcnt lgkmcnt(0)
	v_mfma_f32_32x32x16_bf16 v[0:15], v[152:155], v[156:159], v[0:15]
	ds_read_b64_tr_b16 v[156:157], v205 offset:37888
	ds_read_b64_tr_b16 v[160:161], v205 offset:40960
	ds_read_b64_tr_b16 v[162:163], v205 offset:41472
	ds_read_b64_tr_b16 v[158:159], v205 offset:38400
	v_exp_f32_e32 v107, v107
	v_exp_f32_e32 v108, v108
	v_exp_f32_e32 v109, v109
	v_exp_f32_e32 v110, v110
	v_exp_f32_e32 v111, v111
	s_mov_b32 s46, s44
	s_mov_b32 s47, s44
	s_mov_b32 s45, s44
	v_mov_b64_e32 v[166:167], s[46:47]
	v_mov_b64_e32 v[164:165], s[44:45]
	s_waitcnt lgkmcnt(1)
	v_mfma_f32_32x32x16_bf16 v[16:31], v[152:155], v[160:163], v[16:31]
	v_cvt_pk_bf16_f32 v160, v104, v105
	v_add_f32_e32 v230, v230, v104
	v_add_f32_e32 v252, v252, v105
	v_cvt_pk_bf16_f32 v161, v106, v107
	v_add_f32_e32 v230, v230, v106
	v_add_f32_e32 v252, v252, v107
	v_cvt_pk_bf16_f32 v162, v108, v109
	v_add_f32_e32 v230, v230, v108
	v_add_f32_e32 v252, v252, v109
	v_cvt_pk_bf16_f32 v163, v110, v111
	v_add_f32_e32 v230, v230, v110
	v_add_f32_e32 v252, v252, v111
	v_exp_f32_e32 v112, v112
	v_exp_f32_e32 v113, v113
	v_exp_f32_e32 v114, v114
	ds_read_b64_tr_b16 v[152:153], v205 offset:41984
	ds_read_b64_tr_b16 v[154:155], v205 offset:42496
	v_exp_f32_e32 v115, v115
	v_exp_f32_e32 v116, v116
	v_exp_f32_e32 v117, v117
	v_exp_f32_e32 v118, v118
	v_exp_f32_e32 v119, v119
	v_exp_f32_e32 v120, v120
	s_waitcnt lgkmcnt(2)
	v_mfma_f32_32x32x16_bf16 v[0:15], v[160:163], v[156:159], v[0:15]
	ds_read_b64_tr_b16 v[156:157], v205 offset:38912
	ds_read_b64_tr_b16 v[158:159], v205 offset:39424
	v_exp_f32_e32 v121, v121
	v_exp_f32_e32 v122, v122
	v_exp_f32_e32 v123, v123
	v_exp_f32_e32 v124, v124
	v_exp_f32_e32 v125, v125
	v_exp_f32_e32 v126, v126
	s_waitcnt lgkmcnt(2)
	v_mfma_f32_32x32x16_bf16 v[16:31], v[160:163], v[152:155], v[16:31]
	v_cvt_pk_bf16_f32 v152, v112, v113
	v_add_f32_e32 v230, v230, v112
	v_add_f32_e32 v252, v252, v113
	v_cvt_pk_bf16_f32 v153, v114, v115
	v_add_f32_e32 v230, v230, v114
	v_add_f32_e32 v252, v252, v115
	v_cvt_pk_bf16_f32 v154, v116, v117
	v_add_f32_e32 v230, v230, v116
	v_add_f32_e32 v252, v252, v117
	v_cvt_pk_bf16_f32 v155, v118, v119
	v_add_f32_e32 v230, v230, v118
	v_add_f32_e32 v252, v252, v119
	v_exp_f32_e32 v127, v127
	s_waitcnt lgkmcnt(0)
	v_mfma_f32_32x32x16_bf16 v[0:15], v[152:155], v[156:159], v[0:15]
	ds_read_b64_tr_b16 v[156:157], v205 offset:43008
	ds_read_b64_tr_b16 v[158:159], v205 offset:43520
	ds_read_b64_tr_b16 v[160:161], v205 offset:39936
	ds_read_b64_tr_b16 v[162:163], v205 offset:40448
	s_waitcnt lgkmcnt(2)
	v_mfma_f32_32x32x16_bf16 v[16:31], v[152:155], v[156:159], v[16:31]
	v_cvt_pk_bf16_f32 v156, v120, v121
	v_add_f32_e32 v230, v230, v120
	v_add_f32_e32 v252, v252, v121
	v_cvt_pk_bf16_f32 v157, v122, v123
	v_add_f32_e32 v230, v230, v122
	v_add_f32_e32 v252, v252, v123
	v_cvt_pk_bf16_f32 v158, v124, v125
	v_add_f32_e32 v230, v230, v124
	v_add_f32_e32 v252, v252, v125
	v_cvt_pk_bf16_f32 v159, v126, v127
	v_add_f32_e32 v230, v230, v126
	v_add_f32_e32 v252, v252, v127
	ds_read_b64_tr_b16 v[152:153], v205 offset:44032
	ds_read_b64_tr_b16 v[154:155], v205 offset:44544
	s_waitcnt lgkmcnt(2)
	v_mfma_f32_32x32x16_bf16 v[0:15], v[156:159], v[160:163], v[0:15]
	s_waitcnt lgkmcnt(0)
	v_mfma_f32_32x32x16_bf16 v[16:31], v[156:159], v[152:155], v[16:31]

.Lattn_855i:
	v_lshl_add_u32 v205, s62, 13, v202
	s_waitcnt lgkmcnt(0)
	ds_read_b64_tr_b16 v[156:157], v205 offset:36864
	ds_read_b64_tr_b16 v[158:159], v205 offset:37376
	ds_read_b64_tr_b16 v[164:165], v205 offset:40960
	ds_read_b64_tr_b16 v[166:167], v205 offset:41472
	v_exp_f32_e32 v48, v48
	v_exp_f32_e32 v49, v49
	v_exp_f32_e32 v50, v50
	v_exp_f32_e32 v51, v51
	v_mfma_f32_32x32x16_bf16 v[96:111], v[206:209], v[128:131], v[80:95]
	ds_read_b128 v[206:209], v253 offset:8704
	v_exp_f32_e32 v52, v52
	v_exp_f32_e32 v53, v53
	v_exp_f32_e32 v54, v54
	v_exp_f32_e32 v55, v55
	v_mfma_f32_32x32x16_bf16 v[112:127], v[210:213], v[128:131], v[80:95]
	ds_read_b128 v[210:213], v253 offset:10240
	v_cvt_pk_bf16_f32 v152, v48, v49
	v_add_f32_e32 v230, v230, v48
	v_add_f32_e32 v252, v252, v49
	v_cvt_pk_bf16_f32 v153, v50, v51
	v_mfma_f32_32x32x16_bf16 v[96:111], v[214:217], v[132:135], v[96:111]
	ds_read_b128 v[214:217], v253 offset:10752
	v_add_f32_e32 v230, v230, v50
	v_add_f32_e32 v252, v252, v51
	v_cvt_pk_bf16_f32 v154, v52, v53
	v_add_f32_e32 v230, v230, v52
	v_mfma_f32_32x32x16_bf16 v[112:127], v[218:221], v[132:135], v[112:127]
	v_add_f32_e32 v252, v252, v53
	v_cvt_pk_bf16_f32 v155, v54, v55
	v_add_f32_e32 v230, v230, v54
	v_add_f32_e32 v252, v252, v55
	v_mfma_f32_32x32x16_bf16 v[96:111], v[222:225], v[136:139], v[96:111]
	v_exp_f32_e32 v56, v56
	v_exp_f32_e32 v57, v57
	v_exp_f32_e32 v58, v58
	v_exp_f32_e32 v59, v59
	s_waitcnt lgkmcnt(5)
	v_mfma_f32_32x32x16_bf16 v[0:15], v[152:155], v[156:159], v[0:15]
	ds_read_b64_tr_b16 v[218:219], v205 offset:37888
	ds_read_b64_tr_b16 v[220:221], v205 offset:38400
	ds_read_b64_tr_b16 v[222:223], v205 offset:41984
	ds_read_b64_tr_b16 v[224:225], v205 offset:42496
	v_exp_f32_e32 v60, v60
	v_exp_f32_e32 v61, v61
	v_exp_f32_e32 v62, v62
	v_exp_f32_e32 v63, v63
	s_waitcnt lgkmcnt(7)
	v_mfma_f32_32x32x16_bf16 v[16:31], v[152:155], v[164:167], v[16:31]
	v_cvt_pk_bf16_f32 v160, v56, v57
	v_add_f32_e32 v230, v230, v56
	v_add_f32_e32 v252, v252, v57
	v_cvt_pk_bf16_f32 v161, v58, v59
	v_mfma_f32_32x32x16_bf16 v[112:127], v[226:229], v[136:139], v[112:127]
	ds_read_b64_tr_b16 v[156:157], v205 offset:38912
	ds_read_b64_tr_b16 v[158:159], v205 offset:39424
	ds_read_b64_tr_b16 v[164:165], v205 offset:43008
	ds_read_b64_tr_b16 v[166:167], v205 offset:43520
	v_add_f32_e32 v230, v230, v58
	v_add_f32_e32 v252, v252, v59
	v_cvt_pk_bf16_f32 v162, v60, v61
	v_add_f32_e32 v230, v230, v60
	v_mfma_f32_32x32x16_bf16 v[96:111], v[236:239], v[140:143], v[96:111]
	v_add_f32_e32 v252, v252, v61
	v_cvt_pk_bf16_f32 v163, v62, v63
	v_add_f32_e32 v230, v230, v62
	v_add_f32_e32 v252, v252, v63
	v_mfma_f32_32x32x16_bf16 v[112:127], v[240:243], v[140:143], v[112:127]
	v_exp_f32_e32 v64, v64
	v_exp_f32_e32 v65, v65
	v_exp_f32_e32 v66, v66
	v_exp_f32_e32 v67, v67
	s_waitcnt lgkmcnt(6)
	v_mfma_f32_32x32x16_bf16 v[0:15], v[160:163], v[218:221], v[0:15]
	v_exp_f32_e32 v68, v68
	v_exp_f32_e32 v69, v69
	v_exp_f32_e32 v70, v70
	v_exp_f32_e32 v71, v71
	s_waitcnt lgkmcnt(4)
	v_mfma_f32_32x32x16_bf16 v[16:31], v[160:163], v[222:225], v[16:31]
	v_cvt_pk_bf16_f32 v152, v64, v65
	v_add_f32_e32 v230, v230, v64
	v_add_f32_e32 v252, v252, v65
	v_cvt_pk_bf16_f32 v153, v66, v67
	v_mfma_f32_32x32x16_bf16 v[96:111], v[248:251], v[144:147], v[96:111]
	ds_read_b64_tr_b16 v[218:219], v205 offset:39936
	ds_read_b64_tr_b16 v[220:221], v205 offset:40448
	ds_read_b64_tr_b16 v[222:223], v205 offset:44032
	ds_read_b64_tr_b16 v[224:225], v205 offset:44544
	v_add_f32_e32 v230, v230, v66
	v_add_f32_e32 v252, v252, v67
	v_cvt_pk_bf16_f32 v154, v68, v69
	v_add_f32_e32 v230, v230, v68
	v_mfma_f32_32x32x16_bf16 v[112:127], v[206:209], v[144:147], v[112:127]
	v_add_f32_e32 v252, v252, v69
	v_cvt_pk_bf16_f32 v155, v70, v71
	v_add_f32_e32 v230, v230, v70
	v_add_f32_e32 v252, v252, v71
	s_waitcnt lgkmcnt(6)
	v_mfma_f32_32x32x16_bf16 v[0:15], v[152:155], v[156:159], v[0:15]
	v_exp_f32_e32 v72, v72
	v_exp_f32_e32 v73, v73
	v_exp_f32_e32 v74, v74
	v_exp_f32_e32 v75, v75
	s_waitcnt lgkmcnt(4)
	v_mfma_f32_32x32x16_bf16 v[16:31], v[152:155], v[164:167], v[16:31]
	v_exp_f32_e32 v76, v76
	v_exp_f32_e32 v77, v77
	v_exp_f32_e32 v78, v78
	v_exp_f32_e32 v79, v79
	v_mfma_f32_32x32x16_bf16 v[96:111], v[210:213], v[148:151], v[96:111]
	v_cvt_pk_bf16_f32 v160, v72, v73
	v_add_f32_e32 v230, v230, v72
	v_add_f32_e32 v252, v252, v73
	v_cvt_pk_bf16_f32 v161, v74, v75
	v_mfma_f32_32x32x16_bf16 v[112:127], v[214:217], v[148:151], v[112:127]
	v_add_f32_e32 v230, v230, v74
	v_add_f32_e32 v252, v252, v75
	v_cvt_pk_bf16_f32 v162, v76, v77
	v_add_f32_e32 v230, v230, v76
	v_add_f32_e32 v252, v252, v77
	v_cvt_pk_bf16_f32 v163, v78, v79
	v_add_f32_e32 v230, v230, v78
	v_add_f32_e32 v252, v252, v79
	s_waitcnt lgkmcnt(2)
	v_mfma_f32_32x32x16_bf16 v[0:15], v[160:163], v[218:221], v[0:15]
	s_waitcnt lgkmcnt(0)
	v_mfma_f32_32x32x16_bf16 v[16:31], v[160:163], v[222:225], v[16:31]
	s_branch .Lattn_855_end
.Lattn_869i:
	v_lshl_add_u32 v205, s19, 13, v202
	s_waitcnt lgkmcnt(0)
	ds_read_b64_tr_b16 v[156:157], v205 offset:36864
	ds_read_b64_tr_b16 v[158:159], v205 offset:37376
	ds_read_b64_tr_b16 v[164:165], v205 offset:40960
	ds_read_b64_tr_b16 v[166:167], v205 offset:41472
	v_exp_f32_e32 v96, v96
	v_exp_f32_e32 v97, v97
	v_exp_f32_e32 v98, v98
	v_exp_f32_e32 v99, v99
	v_mfma_f32_32x32x16_bf16 v[48:63], v[206:209], v[128:131], v[80:95]
	ds_read_b128 v[206:209], v253 offset:8704
	v_exp_f32_e32 v100, v100
	v_exp_f32_e32 v101, v101
	v_exp_f32_e32 v102, v102
	v_exp_f32_e32 v103, v103
	v_mfma_f32_32x32x16_bf16 v[64:79], v[210:213], v[128:131], v[80:95]
	ds_read_b128 v[210:213], v253 offset:10240
	v_cvt_pk_bf16_f32 v152, v96, v97
	v_add_f32_e32 v230, v230, v96
	v_add_f32_e32 v252, v252, v97
	v_cvt_pk_bf16_f32 v153, v98, v99
	v_mfma_f32_32x32x16_bf16 v[48:63], v[214:217], v[132:135], v[48:63]
	ds_read_b128 v[214:217], v253 offset:10752
	v_add_f32_e32 v230, v230, v98
	v_add_f32_e32 v252, v252, v99
	v_cvt_pk_bf16_f32 v154, v100, v101
	v_add_f32_e32 v230, v230, v100
	v_mfma_f32_32x32x16_bf16 v[64:79], v[218:221], v[132:135], v[64:79]
	v_add_f32_e32 v252, v252, v101
	v_cvt_pk_bf16_f32 v155, v102, v103
	v_add_f32_e32 v230, v230, v102
	v_add_f32_e32 v252, v252, v103
	v_mfma_f32_32x32x16_bf16 v[48:63], v[222:225], v[136:139], v[48:63]
	v_exp_f32_e32 v104, v104
	v_exp_f32_e32 v105, v105
	v_exp_f32_e32 v106, v106
	v_exp_f32_e32 v107, v107
	s_waitcnt lgkmcnt(5)
	v_mfma_f32_32x32x16_bf16 v[0:15], v[152:155], v[156:159], v[0:15]
	ds_read_b64_tr_b16 v[218:219], v205 offset:37888
	ds_read_b64_tr_b16 v[220:221], v205 offset:38400
	ds_read_b64_tr_b16 v[222:223], v205 offset:41984
	ds_read_b64_tr_b16 v[224:225], v205 offset:42496
	v_exp_f32_e32 v108, v108
	v_exp_f32_e32 v109, v109
	v_exp_f32_e32 v110, v110
	v_exp_f32_e32 v111, v111
	s_waitcnt lgkmcnt(7)
	v_mfma_f32_32x32x16_bf16 v[16:31], v[152:155], v[164:167], v[16:31]
	v_cvt_pk_bf16_f32 v160, v104, v105
	v_add_f32_e32 v230, v230, v104
	v_add_f32_e32 v252, v252, v105
	v_cvt_pk_bf16_f32 v161, v106, v107
	v_mfma_f32_32x32x16_bf16 v[64:79], v[226:229], v[136:139], v[64:79]
	ds_read_b64_tr_b16 v[156:157], v205 offset:38912
	ds_read_b64_tr_b16 v[158:159], v205 offset:39424
	ds_read_b64_tr_b16 v[164:165], v205 offset:43008
	ds_read_b64_tr_b16 v[166:167], v205 offset:43520
	v_add_f32_e32 v230, v230, v106
	v_add_f32_e32 v252, v252, v107
	v_cvt_pk_bf16_f32 v162, v108, v109
	v_add_f32_e32 v230, v230, v108
	v_mfma_f32_32x32x16_bf16 v[48:63], v[236:239], v[140:143], v[48:63]
	v_add_f32_e32 v252, v252, v109
	v_cvt_pk_bf16_f32 v163, v110, v111
	v_add_f32_e32 v230, v230, v110
	v_add_f32_e32 v252, v252, v111
	v_mfma_f32_32x32x16_bf16 v[64:79], v[240:243], v[140:143], v[64:79]
	v_exp_f32_e32 v112, v112
	v_exp_f32_e32 v113, v113
	v_exp_f32_e32 v114, v114
	v_exp_f32_e32 v115, v115
	s_waitcnt lgkmcnt(6)
	v_mfma_f32_32x32x16_bf16 v[0:15], v[160:163], v[218:221], v[0:15]
	v_exp_f32_e32 v116, v116
	v_exp_f32_e32 v117, v117
	v_exp_f32_e32 v118, v118
	v_exp_f32_e32 v119, v119
	s_waitcnt lgkmcnt(4)
	v_mfma_f32_32x32x16_bf16 v[16:31], v[160:163], v[222:225], v[16:31]
	v_cvt_pk_bf16_f32 v152, v112, v113
	v_add_f32_e32 v230, v230, v112
	v_add_f32_e32 v252, v252, v113
	v_cvt_pk_bf16_f32 v153, v114, v115
	v_mfma_f32_32x32x16_bf16 v[48:63], v[248:251], v[144:147], v[48:63]
	ds_read_b64_tr_b16 v[218:219], v205 offset:39936
	ds_read_b64_tr_b16 v[220:221], v205 offset:40448
	ds_read_b64_tr_b16 v[222:223], v205 offset:44032
	ds_read_b64_tr_b16 v[224:225], v205 offset:44544
	v_add_f32_e32 v230, v230, v114
	v_add_f32_e32 v252, v252, v115
	v_cvt_pk_bf16_f32 v154, v116, v117
	v_add_f32_e32 v230, v230, v116
	v_mfma_f32_32x32x16_bf16 v[64:79], v[206:209], v[144:147], v[64:79]
	v_add_f32_e32 v252, v252, v117
	v_cvt_pk_bf16_f32 v155, v118, v119
	v_add_f32_e32 v230, v230, v118
	v_add_f32_e32 v252, v252, v119
	s_waitcnt lgkmcnt(6)
	v_mfma_f32_32x32x16_bf16 v[0:15], v[152:155], v[156:159], v[0:15]
	v_exp_f32_e32 v120, v120
	v_exp_f32_e32 v121, v121
	v_exp_f32_e32 v122, v122
	v_exp_f32_e32 v123, v123
	s_waitcnt lgkmcnt(4)
	v_mfma_f32_32x32x16_bf16 v[16:31], v[152:155], v[164:167], v[16:31]
	v_exp_f32_e32 v124, v124
	v_exp_f32_e32 v125, v125
	v_exp_f32_e32 v126, v126
	v_exp_f32_e32 v127, v127
	v_mfma_f32_32x32x16_bf16 v[48:63], v[210:213], v[148:151], v[48:63]
	v_cvt_pk_bf16_f32 v160, v120, v121
	v_add_f32_e32 v230, v230, v120
	v_add_f32_e32 v252, v252, v121
	v_cvt_pk_bf16_f32 v161, v122, v123
	v_mfma_f32_32x32x16_bf16 v[64:79], v[214:217], v[148:151], v[64:79]
	v_add_f32_e32 v230, v230, v122
	v_add_f32_e32 v252, v252, v123
	v_cvt_pk_bf16_f32 v162, v124, v125
	v_add_f32_e32 v230, v230, v124
	v_add_f32_e32 v252, v252, v125
	v_cvt_pk_bf16_f32 v163, v126, v127
	v_add_f32_e32 v230, v230, v126
	v_add_f32_e32 v252, v252, v127
	s_waitcnt lgkmcnt(2)
	v_mfma_f32_32x32x16_bf16 v[0:15], v[160:163], v[218:221], v[0:15]
	s_waitcnt lgkmcnt(0)
	v_mfma_f32_32x32x16_bf16 v[16:31], v[160:163], v[222:225], v[16:31]
	s_branch .LBB0_870
